# latent-row E-phase loops keep row stores in flight (counted vmcnt 12/8 at the latch, drain only on the per-channel reload path) on top of the K-loop rebalanced version
# speedup vs baseline: 1.0062x; 1.0062x over previous
; DEV float bf2f(unsigned short h) { return __uint_as_float(((unsigned)h) << 16); }
; DEV void e_phase(const Params& p, int l, int mode, int t_begin, int t_end, int widx, int wcount, bool ctxsum) {
;     ...
;   while (t < t_end) {
;     const int mi = t < TL ? (t >> 11) : 8;
;     if (mi != cur_mi) {
;       cur_mi = mi;
;       const float* gate = MOD + (size_t)l * 9 * 9216 + (size_t)mi * 9216 + (3 * sp + 2) * 1024;
;       const float* gp = npost + (l * 3 + sp) * 1024;
;       const float* gpre = npre + (ln * 3 + s) * 1024;
;       const float* mrow = MOD + (size_t)ln * 9 * 9216 + (size_t)mi * 9216;
; #pragma unroll
;       for (int i = 0; i < 4; ++i) { const int c0 = i * 256 + lane * 4;
;         if (mode != 0) { gt[i] = *reinterpret_cast<const f32x4*>(gate + c0); gg[i] = *reinterpret_cast<const f32x4*>(gp + c0); }
;         if (!final_out) { g2[i] = *reinterpret_cast<const f32x4*>(gpre + c0);
;           sh[i] = *reinterpret_cast<const f32x4*>(mrow + (3 * s) * 1024 + c0);
;           sc[i] = *reinterpret_cast<const f32x4*>(mrow + (3 * s + 1) * 1024 + c0); } }
;     }
;     f32x4 xv[4], yv[4];
; #pragma unroll
;     for (int i = 0; i < 4; ++i) { xv[i] = xn[i];
;       if (mode != 0) yv[i] = ctxsum ? (ya[i] + yb[i]) : (f32x4){bf2f(yh[i][0]), bf2f(yh[i][1]), bf2f(yh[i][2]), bf2f(yh[i][3])}; }
;     const int tn = t + 1;
;     if (tn < t_end) LOADROW(tn);
.LBB0_795:
	s_mov_b64 s[50:51], 0x800
	s_mov_b64 s[0:1], 0x1000
	s_waitcnt vmcnt(12)
	v_mov_b64_e32 v[78:79], v[110:111]
	v_mov_b64_e32 v[86:87], v[106:107]
	v_mov_b64_e32 v[90:91], v[102:103]
	v_mov_b64_e32 v[94:95], v[98:99]
	v_lshl_add_u64 v[128:129], v[128:129], 0, s[50:51]
	v_lshl_add_u64 v[130:131], v[130:131], 0, s[0:1]
	v_lshl_add_u64 v[132:133], v[132:133], 0, s[50:51]
	s_and_b64 vcc, exec, s[44:45]
	v_mov_b64_e32 v[80:81], v[112:113]
	v_mov_b64_e32 v[88:89], v[108:109]
	v_mov_b64_e32 v[92:93], v[104:105]
	v_mov_b64_e32 v[96:97], v[100:101]
	s_waitcnt vmcnt(8)
	v_mov_b64_e32 v[134:135], v[148:149]
	v_mov_b64_e32 v[136:137], v[146:147]
	v_mov_b64_e32 v[138:139], v[144:145]
	v_mov_b64_e32 v[140:141], v[142:143]
	s_cbranch_vccnz .LBB0_818

; DEV float bf2f(unsigned short h) { return __uint_as_float(((unsigned)h) << 16); }
; DEV void e_phase(const Params& p, int l, int mode, int t_begin, int t_end, int widx, int wcount, bool ctxsum) {
;     ...
;     const int mi = t < TL ? (t >> 11) : 8;
;     if (mi != cur_mi) {
;       cur_mi = mi;
;       const float* gate = MOD + (size_t)l * 9 * 9216 + (size_t)mi * 9216 + (3 * sp + 2) * 1024;
;       const float* gp = npost + (l * 3 + sp) * 1024;
;       const float* gpre = npre + (ln * 3 + s) * 1024;
;       const float* mrow = MOD + (size_t)ln * 9 * 9216 + (size_t)mi * 9216;
; #pragma unroll
;       for (int i = 0; i < 4; ++i) { const int c0 = i * 256 + lane * 4;
;         if (mode != 0) { gt[i] = *reinterpret_cast<const f32x4*>(gate + c0); gg[i] = *reinterpret_cast<const f32x4*>(gp + c0); }
;         if (!final_out) { g2[i] = *reinterpret_cast<const f32x4*>(gpre + c0);
;           sh[i] = *reinterpret_cast<const f32x4*>(mrow + (3 * s) * 1024 + c0);
;           sc[i] = *reinterpret_cast<const f32x4*>(mrow + (3 * s + 1) * 1024 + c0); } }
;     }
;     f32x4 xv[4], yv[4];
; #pragma unroll
;     for (int i = 0; i < 4; ++i) { xv[i] = xn[i];
;       if (mode != 0) yv[i] = ctxsum ? (ya[i] + yb[i]) : (f32x4){bf2f(yh[i][0]), bf2f(yh[i][1]), bf2f(yh[i][2]), bf2f(yh[i][3])}; }
;     const int tn = t + 1;
;     if (tn < t_end) LOADROW(tn);
.LBB0_803:
	v_lshlrev_b32_e32 v98, 2, v122
	global_load_dwordx4 v[74:77], v98, s[44:45]
	global_load_dwordx4 v[82:85], v[124:125], off offset:3072
	s_and_b64 vcc, exec, s[0:1]
	s_cbranch_vccnz .LBB0_805
	global_load_dwordx4 v[2:5], v[126:127], off offset:3072
	global_load_dwordx4 v[18:21], v0, s[48:49] offset:3072
	global_load_dwordx4 v[34:37], v98, s[50:51]
.LBB0_805:
	s_waitcnt vmcnt(0)
	s_mov_b32 s48, s57
.LBB0_806:
	s_add_i32 s40, s40, 1
	s_cmp_ge_i32 s40, s53
	s_cselect_b64 s[44:45], -1, 0
	s_nop 0
	v_mov_b64_e32 v[112:113], v[80:81]
	v_mov_b64_e32 v[108:109], v[88:89]
	v_mov_b64_e32 v[104:105], v[92:93]
	v_mov_b64_e32 v[100:101], v[96:97]
	s_and_b64 vcc, exec, s[44:45]
	v_lshl_add_u64 v[150:151], s[88:89], 0, v[130:131]
	v_mov_b64_e32 v[110:111], v[78:79]
	v_mov_b64_e32 v[106:107], v[86:87]
	v_mov_b64_e32 v[102:103], v[90:91]
	v_mov_b64_e32 v[98:99], v[94:95]
	s_nop 0
	v_mov_b64_e32 v[148:149], v[134:135]
	v_mov_b64_e32 v[146:147], v[136:137]
	v_mov_b64_e32 v[144:145], v[138:139]
	v_mov_b64_e32 v[142:143], v[140:141]
	s_cbranch_vccnz .LBB0_808
	v_add_co_u32_e32 v110, vcc, 0x63a5000, v150
	v_lshl_add_u64 v[98:99], s[88:89], 0, v[132:133]
	s_nop 0
	v_addc_co_u32_e32 v111, vcc, 0, v151, vcc
	v_add_co_u32_e32 v148, vcc, 0x19ea4000, v98
	s_nop 1
	v_addc_co_u32_e32 v149, vcc, 0, v99, vcc
	global_load_dwordx4 v[98:101], v[110:111], off nt
	global_load_dwordx4 v[102:105], v[110:111], off offset:1024 nt
	global_load_dwordx4 v[106:109], v[110:111], off offset:2048 nt
	s_nop 0
	global_load_dwordx4 v[110:113], v[110:111], off offset:3072 nt
	s_nop 0
	global_load_dwordx2 v[142:143], v[148:149], off offset:2048
	global_load_dwordx2 v[144:145], v[148:149], off offset:2560
	global_load_dwordx2 v[146:147], v[148:149], off offset:3072
	s_nop 0
	global_load_dwordx2 v[148:149], v[148:149], off offset:3584

; DEV void e_phase(const Params& p, int l, int mode, int t_begin, int t_end, int widx, int wcount, bool ctxsum) {
;     ...
;     if (final_out) {
;       if (t < TL) {
; #pragma unroll
;         for (int i = 0; i < 4; ++i) *reinterpret_cast<f32x4*>(p.out + (size_t)t * 1024 + i * 256 + lane * 4) = xv[i];
;       }
.LBB0_816:
	s_andn2_b64 vcc, exec, s[0:1]
	s_cbranch_vccnz .LBB0_795
	v_readlane_b32 s56, v253, 55
	v_readlane_b32 s70, v254, 5
	v_readlane_b32 s71, v254, 6
	v_readlane_b32 s57, v253, 56
	v_readlane_b32 s58, v253, 57
	v_lshl_add_u64 v[134:135], s[70:71], 0, v[130:131]
	v_readlane_b32 s59, v253, 58
	v_readlane_b32 s60, v253, 59
	v_readlane_b32 s61, v253, 60
	v_readlane_b32 s62, v253, 61
	v_readlane_b32 s63, v253, 62
	v_readlane_b32 s64, v253, 63
	v_readlane_b32 s65, v254, 0
	v_readlane_b32 s66, v254, 1
	v_readlane_b32 s67, v254, 2
	v_readlane_b32 s68, v254, 3
	v_readlane_b32 s69, v254, 4
	global_store_dwordx4 v[134:135], v[94:97], off
	global_store_dwordx4 v[134:135], v[90:93], off offset:1024
	global_store_dwordx4 v[134:135], v[86:89], off offset:2048
	global_store_dwordx4 v[134:135], v[78:81], off offset:3072
	s_waitcnt vmcnt(0)
	s_branch .LBB0_795

; DEV float bf2f(unsigned short h) { return __uint_as_float(((unsigned)h) << 16); }
; DEV void e_phase(const Params& p, int l, int mode, int t_begin, int t_end, int widx, int wcount, bool ctxsum) {
;     ...
;     f32x4 xv[4], yv[4];
; #pragma unroll
;     for (int i = 0; i < 4; ++i) { xv[i] = xn[i];
;       if (mode != 0) yv[i] = ctxsum ? (ya[i] + yb[i]) : (f32x4){bf2f(yh[i][0]), bf2f(yh[i][1]), bf2f(yh[i][2]), bf2f(yh[i][3])}; }
;     const int tn = t + 1;
;     if (tn < t_end) LOADROW(tn);
.LBB0_913:
	s_mov_b64 s[38:39], 0x800
	s_mov_b64 s[0:1], 0x1000
	s_waitcnt vmcnt(12)
	v_mov_b64_e32 v[82:83], v[110:111]
	v_mov_b64_e32 v[86:87], v[106:107]
	v_mov_b64_e32 v[90:91], v[102:103]
	v_mov_b64_e32 v[94:95], v[98:99]
	v_lshl_add_u64 v[128:129], v[128:129], 0, s[38:39]
	v_lshl_add_u64 v[130:131], v[130:131], 0, s[0:1]
	v_lshl_add_u64 v[132:133], v[132:133], 0, s[38:39]
	s_and_b64 vcc, exec, s[44:45]
	v_mov_b64_e32 v[84:85], v[112:113]
	v_mov_b64_e32 v[88:89], v[108:109]
	v_mov_b64_e32 v[92:93], v[104:105]
	v_mov_b64_e32 v[96:97], v[100:101]
	s_waitcnt vmcnt(8)
	v_mov_b64_e32 v[134:135], v[148:149]
	v_mov_b64_e32 v[136:137], v[146:147]
	v_mov_b64_e32 v[138:139], v[144:145]
	v_mov_b64_e32 v[140:141], v[142:143]
	s_cbranch_vccnz .LBB0_936

; DEV float bf2f(unsigned short h) { return __uint_as_float(((unsigned)h) << 16); }
; DEV void e_phase(const Params& p, int l, int mode, int t_begin, int t_end, int widx, int wcount, bool ctxsum) {
;     ...
;     f32x4 xv[4], yv[4];
; #pragma unroll
;     for (int i = 0; i < 4; ++i) { xv[i] = xn[i];
;       if (mode != 0) yv[i] = ctxsum ? (ya[i] + yb[i]) : (f32x4){bf2f(yh[i][0]), bf2f(yh[i][1]), bf2f(yh[i][2]), bf2f(yh[i][3])}; }
;     const int tn = t + 1;
;     if (tn < t_end) LOADROW(tn);
.LBB0_923:
	s_waitcnt vmcnt(0)
	s_mov_b32 s48, s56
.LBB0_924:
	s_add_i32 s40, s40, 1
	s_cmp_ge_i32 s40, s53
	s_cselect_b64 s[44:45], -1, 0
	s_nop 0
	v_mov_b64_e32 v[112:113], v[84:85]
	v_mov_b64_e32 v[108:109], v[88:89]
	v_mov_b64_e32 v[104:105], v[92:93]
	v_mov_b64_e32 v[100:101], v[96:97]
	s_and_b64 vcc, exec, s[44:45]
	v_lshl_add_u64 v[150:151], s[88:89], 0, v[130:131]
	v_mov_b64_e32 v[110:111], v[82:83]
	v_mov_b64_e32 v[106:107], v[86:87]
	v_mov_b64_e32 v[102:103], v[90:91]
	v_mov_b64_e32 v[98:99], v[94:95]
	s_nop 0
	v_mov_b64_e32 v[148:149], v[134:135]
	v_mov_b64_e32 v[146:147], v[136:137]
	v_mov_b64_e32 v[144:145], v[138:139]
	v_mov_b64_e32 v[142:143], v[140:141]
	s_cbranch_vccnz .LBB0_926
	v_add_co_u32_e32 v110, vcc, 0x63a5000, v150
	v_lshl_add_u64 v[98:99], s[88:89], 0, v[132:133]
	s_nop 0
	v_addc_co_u32_e32 v111, vcc, 0, v151, vcc
	v_add_co_u32_e32 v148, vcc, 0x19ea4000, v98
	s_nop 1
	v_addc_co_u32_e32 v149, vcc, 0, v99, vcc
	global_load_dwordx4 v[98:101], v[110:111], off nt
	global_load_dwordx4 v[102:105], v[110:111], off offset:1024 nt
	global_load_dwordx4 v[106:109], v[110:111], off offset:2048 nt
	s_nop 0
	global_load_dwordx4 v[110:113], v[110:111], off offset:3072 nt
	s_nop 0
	global_load_dwordx2 v[142:143], v[148:149], off offset:2048
	global_load_dwordx2 v[144:145], v[148:149], off offset:2560
	global_load_dwordx2 v[146:147], v[148:149], off offset:3072
	s_nop 0
	global_load_dwordx2 v[148:149], v[148:149], off offset:3584

; DEV void e_phase(const Params& p, int l, int mode, int t_begin, int t_end, int widx, int wcount, bool ctxsum) {
;     ...
;     if (final_out) {
;       if (t < TL) {
; #pragma unroll
;         for (int i = 0; i < 4; ++i) *reinterpret_cast<f32x4*>(p.out + (size_t)t * 1024 + i * 256 + lane * 4) = xv[i];
;       }
.LBB0_934:
	s_andn2_b64 vcc, exec, s[0:1]
	s_cbranch_vccnz .LBB0_913
	v_readlane_b32 s56, v253, 55
	v_readlane_b32 s70, v254, 5
	v_readlane_b32 s71, v254, 6
	v_readlane_b32 s57, v253, 56
	v_readlane_b32 s58, v253, 57
	v_lshl_add_u64 v[134:135], s[70:71], 0, v[130:131]
	v_readlane_b32 s59, v253, 58
	v_readlane_b32 s60, v253, 59
	v_readlane_b32 s61, v253, 60
	v_readlane_b32 s62, v253, 61
	v_readlane_b32 s63, v253, 62
	v_readlane_b32 s64, v253, 63
	v_readlane_b32 s65, v254, 0
	v_readlane_b32 s66, v254, 1
	v_readlane_b32 s67, v254, 2
	v_readlane_b32 s68, v254, 3
	v_readlane_b32 s69, v254, 4
	global_store_dwordx4 v[134:135], v[94:97], off
	global_store_dwordx4 v[134:135], v[90:93], off offset:1024
	global_store_dwordx4 v[134:135], v[86:89], off offset:2048
	global_store_dwordx4 v[134:135], v[82:85], off offset:3072
	s_waitcnt vmcnt(0)
	s_branch .LBB0_913
